# speedup vs baseline: 1.0015x; 1.0015x over previous
; #define LRU_LOAD_X(ch) do { _Pragma("unroll") for (int i_ = 0; i_ < 11; ++i_) { const int t_ = (ch) * 64 + 8 * tg - 3 + i_;            \
;         px[i_] = t_ >= 0 ? *(const unsigned*)(p.proj + (size_t)t_ * LDP + C_LX + c0 + 2 * c2) : 0u; } } while (0)
; DI void lru_unit(const PP& p, int l, int nb, int seg, int pass, char* lds, bool dummy = false) {
;     ...
;     const int gch = c0 + 32 * nt + r32;
;     const float gba = p.b_a[l * 1024 + gch], gbx = p.b_x[l * 1024 + gch];
;     const float lamv = p.lam[l * 1024 + gch];
;     const float spl = (lamv > 0.f ? 0.f : -lamv) + __logf(1.f + __expf(-fabsf(lamv)));
;     const int c2 = tid & 63, tg = tid >> 6;
;     float cw[4][2], cb[2];
; #pragma unroll
;     for (int i = 0; i < 4; ++i) { cw[i][0] = p.conv_w[(l * 4 + i) * 1024 + c0 + 2 * c2]; cw[i][1] = p.conv_w[(l * 4 + i) * 1024 + c0 + 2 * c2 + 1]; }
;     cb[0] = p.conv_b[l * 1024 + c0 + 2 * c2]; cb[1] = p.conv_b[l * 1024 + c0 + 2 * c2 + 1];
;     unsigned px[11];
;     ...
;     const int ch0 = seg * SEGC, ch1 = ch0 + SEGC;
;     LRU_LOAD_X(ch0);
;     float hprev = 0.f, atot = 1.f;
;     const int sc_ = tid & 127, sg = tid >> 7;
;     if (pass == 2)
;         for (int j = 0; j < seg; ++j) hprev = p.lstate[((nb * NSEG + j) * 2 + 0) * 128 + sc_] * hprev + p.lstate[((nb * NSEG + j) * 2 + 1) * 128 + sc_];
;     u32x4 ply[2];
.LBB0_459:
	s_mov_b32 s0, 0xbfb8aa3b
	s_waitcnt vmcnt(5)
	v_mul_f32_e64 v3, |v13|, s0
	v_exp_f32_e32 v3, v3
	v_cmp_nlt_f32_e64 s[0:1], 0, v13
	v_lshlrev_b32_e32 v2, 3, v8
	v_readlane_b32 s2, v254, 14
	v_add_f32_e32 v3, 1.0, v3
	v_cmp_gt_f32_e32 vcc, s66, v3
	v_cndmask_b32_e64 v13, 0, -v13, s[0:1]
	s_mov_b32 s0, 0x3f317217
	v_cndmask_b32_e64 v15, 0, 32, vcc
	v_ldexp_f32 v3, v3, v15
	v_log_f32_e32 v3, v3
	v_mov_b32_e32 v15, 0x41b17218
	v_cndmask_b32_e32 v15, 0, v15, vcc
	v_readlane_b32 s1, v254, 13
	v_mul_f32_e32 v16, 0x3f317217, v3
	v_fma_f32 v16, v3, s0, -v16
	v_fmac_f32_e32 v16, 0x3377d1cf, v3
	s_mov_b32 s0, 0x7f800000
	v_fmac_f32_e32 v16, 0x3f317217, v3
	v_cmp_lt_f32_e64 vcc, |v3|, s0
	v_add_u32_e32 v25, 0x200, v5
	s_movk_i32 s0, 0x110
	v_cndmask_b32_e32 v3, v3, v16, vcc
	v_sub_f32_e32 v3, v3, v15
	v_ashrrev_i32_e32 v15, 8, v5
	v_lshl_or_b32 v16, v15, 5, v7
	v_lshlrev_b32_e32 v15, 12, v15
	v_lshl_or_b32 v8, v8, 9, v15
	v_add_f32_e32 v116, v13, v3
	v_ashrrev_i32_e32 v3, 7, v5
	v_or3_b32 v7, v10, v8, v7
	v_lshlrev_b32_e32 v8, 2, v5
	v_lshl_add_u32 v13, v2, 1, 0
	v_lshlrev_b32_e32 v2, 2, v14
	v_add_u32_e32 v133, s1, v8
	v_add_u32_e32 v134, s2, v8
	v_lshlrev_b32_e32 v8, 13, v3
	v_lshl_add_u32 v136, v7, 2, 0
	v_or_b32_e32 v7, v8, v2
	v_add_u32_e32 v137, 0, v7
	v_or_b32_e32 v7, 0x200, v2
	v_add_u32_e32 v14, 0, v2
	v_or_b32_e32 v17, 1, v12
	v_ashrrev_i32_e32 v25, 4, v25
	v_add_u32_e32 v138, s1, v2
	v_add_u32_e32 v139, s2, v2
	v_add_u32_e32 v140, s1, v7
	v_add_u32_e32 v141, s2, v7
	v_or_b32_e32 v7, 0x400, v2
	v_or_b32_e32 v2, 0x600, v2
	v_mul_lo_u32 v16, v16, s0
	v_mul_lo_u32 v18, v17, s0
	v_add_u32_e32 v144, s1, v2
	v_add_u32_e32 v145, s2, v2
	s_movk_i32 s0, 0x80
	v_add_u32_e32 v2, s6, v25
	s_lshl_b32 s7, s24, 5
	v_add_u32_e32 v142, s1, v7
	v_cmp_eq_u32_e64 s[36:37], 3, v3
	v_cmp_eq_u32_e64 s[38:39], 2, v3
	v_cmp_eq_u32_e64 s[40:41], 1, v3
	v_cmp_gt_u32_e64 s[42:43], s0, v5
	v_mad_i64_i32 v[2:3], s[0:1], v2, s35, 0
	s_add_i32 s5, s7, 32
	v_lshlrev_b32_e32 v10, 5, v4
	v_add_u32_e32 v143, s2, v7
	v_lshlrev_b32_e32 v4, 4, v4
	s_lshl_b64 s[0:1], s[22:23], 1
	v_readlane_b32 s2, v254, 9
	v_and_b32_e32 v4, 0xf0, v4
	s_add_u32 s0, s2, s0
	v_readlane_b32 s2, v254, 10
	v_ashrrev_i32_e32 v24, 4, v5
	v_or_b32_e32 v2, v2, v4
	s_addc_u32 s1, s2, s1
	s_movk_i32 s3, 0x880
	v_lshl_add_u64 v[118:119], s[0:1], 0, v[2:3]
	v_add_u32_e32 v2, s6, v24
	v_lshl_add_u32 v11, v11, 1, 0
	v_and_b32_e32 v10, 0x1e0, v10
	v_mul_lo_u32 v15, v6, s3
	v_lshlrev_b32_e32 v12, 9, v12
	v_mad_i64_i32 v[2:3], s[2:3], v2, s35, 0
	v_lshl_add_u32 v9, v9, 2, v11
	v_add_u32_e32 v10, 0, v10
	v_lshlrev_b32_e32 v6, 12, v6
	v_lshlrev_b32_e32 v17, 9, v17
	v_or_b32_e32 v19, 0x400, v12
	v_or_b32_e32 v20, 0x600, v12
	v_or_b32_e32 v21, 0x800, v12
	v_or_b32_e32 v22, 0xa00, v12
	v_or_b32_e32 v23, 0xc00, v12
	v_or_b32_e32 v12, 0xe00, v12
	v_lshlrev_b32_e32 v5, 9, v24
	v_lshlrev_b32_e32 v7, 9, v25
	v_or_b32_e32 v2, v2, v4
	s_mov_b32 s4, 0
	v_mov_b32_e32 v117, v116
	v_lshl_add_u64 v[120:121], s[0:1], 0, v[2:3]
	s_or_b32 s6, s7, 1
	v_add_u32_e32 v147, v11, v15
	v_add_u32_e32 v148, v9, v6
	v_add_u32_e32 v149, v11, v18
	v_add_u32_e32 v150, v9, v17
	v_add_u32_e32 v151, v9, v19
	v_add_u32_e32 v152, v9, v20
	v_add_u32_e32 v153, v9, v21
	v_add_u32_e32 v154, v9, v22
	v_add_u32_e32 v155, v9, v23
	v_add_u32_e32 v156, v9, v12
	v_add_u32_e32 v157, v13, v16
	v_add_u32_e32 v158, v14, v8
	v_add_u32_e32 v159, v10, v5
	v_add_u32_e32 v160, v10, v7
	s_waitcnt vmcnt(0)
	s_branch .LBB0_462

; DI float bflo(unsigned w) { return __uint_as_float(w << 16); }
; DI float bfhi(unsigned w) { return __uint_as_float(w & 0xffff0000u); }
; DI unsigned cvtpk(float lo, float hi) { unsigned r; asm volatile("v_cvt_pk_bf16_f32 %0, %1, %2" : "=v"(r) : "v"(lo), "v"(hi)); return r; }
; #define LRU_LOAD_X(ch) do { _Pragma("unroll") for (int i_ = 0; i_ < 11; ++i_) { const int t_ = (ch) * 64 + 8 * tg - 3 + i_;            \
;         px[i_] = t_ >= 0 ? *(const unsigned*)(p.proj + (size_t)t_ * LDP + C_LX + c0 + 2 * c2) : 0u; } } while (0)
; DI void lru_unit(const PP& p, int l, int nb, int seg, int pass, char* lds, bool dummy = false) {
;     ...
;     for (int ch = ch0; ch < ch1; ++ch) {
; #pragma unroll
;         for (int t = 0; t < 8; ++t) {
;             float u0 = cb[0], u1 = cb[1];
; #pragma unroll
;             for (int i = 0; i < 4; ++i) { u0 += cw[i][0] * bflo(px[t + i]); u1 += cw[i][1] * bfhi(px[t + i]); }
;             const int tok = 8 * tg + t;
;             *(unsigned*)(Us + tok * 136 + 2 * c2) = cvtpk(u0, u1);
;             *(f32x2*)(Uf + tok * 128 + 2 * c2) = (f32x2){u0, u1};
;         }
;         __syncthreads();
;         if (ch + 1 < ch1) LRU_LOAD_X(ch + 1);
.LBB0_462:
	s_nop 0
	v_lshlrev_b32_e32 v2, 16, v124
	v_and_b32_e32 v3, 0xffff0000, v124
	v_lshlrev_b32_e32 v4, 16, v125
	v_and_b32_e32 v5, 0xffff0000, v125
	v_pk_fma_f32 v[2:3], v[106:107], v[2:3], v[114:115]
	v_lshlrev_b32_e32 v6, 16, v127
	v_and_b32_e32 v7, 0xffff0000, v127
	v_pk_fma_f32 v[2:3], v[108:109], v[4:5], v[2:3]
	v_lshlrev_b32_e32 v8, 16, v128
	v_and_b32_e32 v9, 0xffff0000, v128
	v_pk_fma_f32 v[2:3], v[110:111], v[6:7], v[2:3]
	v_pk_fma_f32 v[4:5], v[106:107], v[4:5], v[114:115]
	v_pk_fma_f32 v[2:3], v[112:113], v[8:9], v[2:3]
	v_pk_fma_f32 v[4:5], v[108:109], v[6:7], v[4:5]
	v_cvt_pk_bf16_f32 v10, v2, v3
	ds_write_b32 v147, v10
	ds_write_b64 v148, v[2:3] offset:17408
	v_lshlrev_b32_e32 v2, 16, v129
	v_and_b32_e32 v3, 0xffff0000, v129
	v_pk_fma_f32 v[4:5], v[110:111], v[8:9], v[4:5]
	v_pk_fma_f32 v[6:7], v[106:107], v[6:7], v[114:115]
	v_pk_fma_f32 v[4:5], v[112:113], v[2:3], v[4:5]
	v_pk_fma_f32 v[6:7], v[108:109], v[8:9], v[6:7]
	v_cvt_pk_bf16_f32 v10, v4, v5
	ds_write_b32 v149, v10
	ds_write_b64 v150, v[4:5] offset:17408
	v_lshlrev_b32_e32 v4, 16, v130
	v_and_b32_e32 v5, 0xffff0000, v130
	v_pk_fma_f32 v[6:7], v[110:111], v[2:3], v[6:7]
	v_pk_fma_f32 v[8:9], v[106:107], v[8:9], v[114:115]
	v_pk_fma_f32 v[6:7], v[112:113], v[4:5], v[6:7]
	v_pk_fma_f32 v[8:9], v[108:109], v[2:3], v[8:9]
	v_cvt_pk_bf16_f32 v10, v6, v7
	ds_write_b32 v149, v10 offset:272
	ds_write_b64 v151, v[6:7] offset:17408
	v_lshlrev_b32_e32 v6, 16, v131
	v_and_b32_e32 v7, 0xffff0000, v131
	v_pk_fma_f32 v[8:9], v[110:111], v[4:5], v[8:9]
	v_pk_fma_f32 v[2:3], v[106:107], v[2:3], v[114:115]
	v_pk_fma_f32 v[8:9], v[112:113], v[6:7], v[8:9]
	v_pk_fma_f32 v[2:3], v[108:109], v[4:5], v[2:3]
	v_cvt_pk_bf16_f32 v10, v8, v9
	ds_write_b32 v149, v10 offset:544
	ds_write_b64 v152, v[8:9] offset:17408
	v_lshlrev_b32_e32 v8, 16, v132
	v_and_b32_e32 v9, 0xffff0000, v132
	v_pk_fma_f32 v[2:3], v[110:111], v[6:7], v[2:3]
	v_pk_fma_f32 v[4:5], v[106:107], v[4:5], v[114:115]
	v_pk_fma_f32 v[2:3], v[112:113], v[8:9], v[2:3]
	v_pk_fma_f32 v[4:5], v[108:109], v[6:7], v[4:5]
	v_cvt_pk_bf16_f32 v10, v2, v3
	ds_write_b32 v149, v10 offset:816
	ds_write_b64 v153, v[2:3] offset:17408
	v_lshlrev_b32_e32 v2, 16, v135
	v_and_b32_e32 v3, 0xffff0000, v135
	v_pk_fma_f32 v[4:5], v[110:111], v[8:9], v[4:5]
	v_pk_fma_f32 v[6:7], v[106:107], v[6:7], v[114:115]
	v_pk_fma_f32 v[4:5], v[112:113], v[2:3], v[4:5]
	v_pk_fma_f32 v[6:7], v[108:109], v[8:9], v[6:7]
	v_cvt_pk_bf16_f32 v10, v4, v5
	ds_write_b32 v149, v10 offset:1088
	ds_write_b64 v154, v[4:5] offset:17408
	v_lshlrev_b32_e32 v4, 16, v146
	v_and_b32_e32 v5, 0xffff0000, v146
	v_pk_fma_f32 v[6:7], v[110:111], v[2:3], v[6:7]
	v_pk_fma_f32 v[8:9], v[106:107], v[8:9], v[114:115]
	v_pk_fma_f32 v[6:7], v[112:113], v[4:5], v[6:7]
	v_pk_fma_f32 v[2:3], v[108:109], v[2:3], v[8:9]
	v_cvt_pk_bf16_f32 v10, v6, v7
	ds_write_b32 v149, v10 offset:1360
	ds_write_b64 v155, v[6:7] offset:17408
	v_lshlrev_b32_e32 v6, 16, v161
	v_and_b32_e32 v7, 0xffff0000, v161
	v_pk_fma_f32 v[2:3], v[110:111], v[4:5], v[2:3]
	s_cmp_ge_u32 s6, s5
	v_pk_fma_f32 v[2:3], v[112:113], v[6:7], v[2:3]
	s_nop 0
	v_cvt_pk_bf16_f32 v4, v2, v3
	ds_write_b32 v149, v4 offset:1632
	ds_write_b64 v156, v[2:3] offset:17408
	s_waitcnt lgkmcnt(0)
	s_barrier
	s_cbranch_scc1 .LBB0_461
	v_add_u32_e32 v2, s4, v126
	s_lshl_b32 s10, s22, 1
	s_addk_i32 s10, 0x1800
	v_add_u32_e32 v5, s10, v0
	v_add_u32_e32 v4, 61, v2
	v_mad_u32_u24 v4, v4, s35, v5
	global_load_dword v124, v4, s[86:87]
	v_add_u32_e32 v4, 62, v2
	v_mad_u32_u24 v4, v4, s35, v5
	global_load_dword v125, v4, s[86:87]
	v_add_u32_e32 v4, 63, v2
	v_mad_u32_u24 v4, v4, s35, v5
	global_load_dword v127, v4, s[86:87]
	v_add_u32_e32 v4, 64, v2
	v_mad_u32_u24 v4, v4, s35, v5
	global_load_dword v128, v4, s[86:87]
	v_add_u32_e32 v4, 65, v2
	v_mad_u32_u24 v4, v4, s35, v5
	global_load_dword v129, v4, s[86:87]
	v_add_u32_e32 v4, 66, v2
	v_mad_u32_u24 v4, v4, s35, v5
	global_load_dword v130, v4, s[86:87]
	v_add_u32_e32 v4, 67, v2
	v_mad_u32_u24 v4, v4, s35, v5
	global_load_dword v131, v4, s[86:87]
	v_add_u32_e32 v4, 68, v2
	v_mad_u32_u24 v4, v4, s35, v5
	global_load_dword v132, v4, s[86:87]
	v_add_u32_e32 v4, 69, v2
	v_mad_u32_u24 v4, v4, s35, v5
	global_load_dword v135, v4, s[86:87]
	v_add_u32_e32 v4, 70, v2
	v_mad_u32_u24 v4, v4, s35, v5
	global_load_dword v146, v4, s[86:87]
	v_add_u32_e32 v4, 71, v2
	v_mad_u32_u24 v4, v4, s35, v5
	global_load_dword v161, v4, s[86:87]
	s_branch .LBB0_461
